# as v27 plus gate/up K-loop: last two LDS-DMA issues of each heavy load segment moved into the wave's own MFMA segment (vmcnt 8->6)
# baseline (speedup 1.0000x reference)
; #define PG8_STAGE(bufoff, gbase, voff) do { _Pragma("unroll") for (int _i = 0; _i < 2; ++_i) \
;         __builtin_amdgcn_global_load_lds((const unsigned*)((const char*)(gbase) + (voff)[_i]), (LAS unsigned*)(lds + (bufoff) + ldsw + _i * 8192), 16, 0, 0); } while (0)
; #define PG8_LDA(dst, b, h) do { _Pragma("unroll") for (int m = 0; m < 4; ++m) _Pragma("unroll") for (int k = 0; k < 2; ++k) dst[m][k] = *(const LAS bf16x8*)(lds + PG8_SA(b, h) + aoff + m * 2048 + k * 1024); } while (0)
; #define PG8_LDB(dst, b, h) do { _Pragma("unroll") for (int n = 0; n < 2; ++n) _Pragma("unroll") for (int k = 0; k < 2; ++k) dst[n][k] = *(const LAS bf16x8*)(lds + PG8_SB(b, h) + boff + n * 2048 + k * 1024); } while (0)
; #define PG8_MMA(ai, bj, At, Bt) do { __builtin_amdgcn_s_setprio(1); _Pragma("unroll") for (int m = 0; m < 4; ++m) _Pragma("unroll") for (int n = 0; n < 2; ++n) _Pragma("unroll") for (int k = 0; k < 2; ++k) \
;         acc[ai][bj][m][n] = __builtin_amdgcn_mfma_f32_16x16x32_bf16(Bt[n][k], At[m][k], acc[ai][bj][m][n], 0, 0, 0); __builtin_amdgcn_s_setprio(0); } while (0)
; #define PG8_WAIT_V(n) asm volatile("s_waitcnt vmcnt(" #n ")" ::: "memory")
; #define PG8_WAIT_L(n) asm volatile("s_waitcnt lgkmcnt(" #n ")" ::: "memory")
; #define PG8_BAR __builtin_amdgcn_s_barrier()
; #define PG8_SCHED __builtin_amdgcn_sched_barrier(0)
; template <class Epi, bool ALIGN_EPI>
; __device__ __forceinline__ void gemm_phase(LAS unsigned char* lds, const Gemm g, const StaticOrder S, const Epi E) {
;     ...
;         for (int t = 0; t < nt; t += 2) {
;             const bool last = (t == nt - 2);
;             const char* a1 = cA + (size_t)(t + 1) * kstep;
;             const char* a2 = last ? nA : cA + (size_t)(t + 2) * kstep; const char* b2 = last ? nB : cB + (size_t)(t + 2) * kstep;
;             const char* a3 = a2 + kstep; const char* b3 = b2 + kstep;
;             PG8_LDB(B0, 0, 0); PG8_LDB(B1, 0, 1); PG8_SCHED; PG8_LDA(At, 0, 0); PG8_STAGE(PG8_SA(1, 1), a1 + hstepA, voffA);
;             PG8_WAIT_V(8); PG8_WAIT_L(0); PG8_BAR; PG8_MMA(0, 0, At, B0); PG8_MMA(0, 1, At, B1); PG8_BAR; PG8_SCHED;
;             PG8_LDA(At, 0, 1); PG8_STAGE(PG8_SB(0, 0), b2, voffB); PG8_STAGE(PG8_SB(0, 1), b2 + hstepB, voffB); PG8_STAGE(PG8_SA(0, 0), a2, voffA);
;             PG8_WAIT_V(8); PG8_WAIT_L(0); PG8_BAR; PG8_MMA(1, 0, At, B0); PG8_MMA(1, 1, At, B1); PG8_BAR; PG8_SCHED;
.LBB0_604:
	s_add_u32 s0, s40, 0xfffc0080
	s_addc_u32 s1, s41, -1
	s_add_i32 s12, 0, 0x10000
	s_cmp_eq_u32 s54, 12
	s_cselect_b32 s49, s34, s1
	s_cselect_b32 s48, s35, s0
	v_add_u32_e32 v130, s12, v172
	s_cselect_b32 s47, s50, s53
	s_cselect_b32 s46, s51, s52
	s_add_i32 s15, 0, 0x14000
	ds_read_b128 v[182:185], v130
	ds_read_b128 v[186:189], v130 offset:1024
	ds_read_b128 v[190:193], v130 offset:2048
	ds_read_b128 v[194:197], v130 offset:3072
	v_add_u32_e32 v130, s15, v172
	ds_read_b128 v[198:201], v130
	ds_read_b128 v[202:205], v130 offset:1024
	ds_read_b128 v[206:209], v130 offset:2048
	ds_read_b128 v[210:213], v130 offset:3072
	v_lshl_add_u64 v[164:165], s[40:41], 0, v[150:151]
	s_add_i32 m0, s24, 0xc000
	ds_read_b128 v[214:217], v173
	ds_read_b128 v[218:221], v173 offset:1024
	ds_read_b128 v[222:225], v173 offset:2048
	ds_read_b128 v[226:229], v173 offset:3072
	ds_read_b128 v[230:233], v173 offset:4096
	ds_read_b128 v[234:237], v173 offset:5120
	ds_read_b128 v[238:241], v173 offset:6144
	ds_read_b128 v[242:245], v173 offset:7168
	global_load_lds_dwordx4 v[164:165], off
	v_lshl_add_u64 v[164:165], s[40:41], 0, v[152:153]
	s_add_i32 m0, s24, 0xe000
	s_nop 0
	global_load_lds_dwordx4 v[164:165], off
	s_waitcnt vmcnt(8)
	s_waitcnt lgkmcnt(0)
	s_barrier
	s_setprio 1
	s_waitcnt lgkmcnt(0)
	v_mfma_f32_16x16x32_bf16 v[126:129], v[182:185], v[214:217], v[126:129]
	v_mfma_f32_16x16x32_bf16 v[118:121], v[190:193], v[214:217], v[118:121]
	v_mfma_f32_16x16x32_bf16 v[110:113], v[182:185], v[222:225], v[110:113]
	v_mfma_f32_16x16x32_bf16 v[106:109], v[190:193], v[222:225], v[106:109]
	v_mfma_f32_16x16x32_bf16 v[94:97], v[182:185], v[230:233], v[94:97]
	v_mfma_f32_16x16x32_bf16 v[86:89], v[190:193], v[230:233], v[86:89]
	v_mfma_f32_16x16x32_bf16 v[76:79], v[182:185], v[238:241], v[76:79]
	v_mfma_f32_16x16x32_bf16 v[72:75], v[190:193], v[238:241], v[72:75]
	v_mfma_f32_16x16x32_bf16 v[126:129], v[186:189], v[218:221], v[126:129]
	v_mfma_f32_16x16x32_bf16 v[118:121], v[194:197], v[218:221], v[118:121]
	v_mfma_f32_16x16x32_bf16 v[110:113], v[186:189], v[226:229], v[110:113]
	v_mfma_f32_16x16x32_bf16 v[106:109], v[194:197], v[226:229], v[106:109]
	v_mfma_f32_16x16x32_bf16 v[94:97], v[186:189], v[234:237], v[94:97]
	v_mfma_f32_16x16x32_bf16 v[86:89], v[194:197], v[234:237], v[86:89]
	v_mfma_f32_16x16x32_bf16 v[76:79], v[186:189], v[242:245], v[76:79]
	v_mfma_f32_16x16x32_bf16 v[72:75], v[194:197], v[242:245], v[72:75]
	s_setprio 0
	s_setprio 1
	v_mfma_f32_16x16x32_bf16 v[122:125], v[198:201], v[214:217], v[122:125]
	v_mfma_f32_16x16x32_bf16 v[114:117], v[206:209], v[214:217], v[114:117]
	v_mfma_f32_16x16x32_bf16 v[102:105], v[198:201], v[222:225], v[102:105]
	v_mfma_f32_16x16x32_bf16 v[98:101], v[206:209], v[222:225], v[98:101]
	v_mfma_f32_16x16x32_bf16 v[90:93], v[198:201], v[230:233], v[90:93]
	v_mfma_f32_16x16x32_bf16 v[82:85], v[206:209], v[230:233], v[82:85]
	v_mfma_f32_16x16x32_bf16 v[68:71], v[198:201], v[238:241], v[68:71]
	v_mfma_f32_16x16x32_bf16 v[64:67], v[206:209], v[238:241], v[64:67]
	v_mfma_f32_16x16x32_bf16 v[122:125], v[202:205], v[218:221], v[122:125]
	v_mfma_f32_16x16x32_bf16 v[114:117], v[210:213], v[218:221], v[114:117]
	v_mfma_f32_16x16x32_bf16 v[102:105], v[202:205], v[226:229], v[102:105]
	v_mfma_f32_16x16x32_bf16 v[98:101], v[210:213], v[226:229], v[98:101]
	v_mfma_f32_16x16x32_bf16 v[90:93], v[202:205], v[234:237], v[90:93]
	v_mfma_f32_16x16x32_bf16 v[82:85], v[210:213], v[234:237], v[82:85]
	v_mfma_f32_16x16x32_bf16 v[68:71], v[202:205], v[242:245], v[68:71]
	v_mfma_f32_16x16x32_bf16 v[64:67], v[210:213], v[242:245], v[64:67]
	s_setprio 0
	s_barrier
	s_add_i32 s0, s12, s73
	v_lshl_add_u64 v[164:165], s[46:47], 0, v[80:81]
	s_mov_b32 m0, s0
	ds_read_b128 v[214:217], v173 offset:16384
	ds_read_b128 v[218:221], v173 offset:17408
	ds_read_b128 v[222:225], v173 offset:18432
	ds_read_b128 v[226:229], v173 offset:19456
	ds_read_b128 v[230:233], v173 offset:20480
	ds_read_b128 v[234:237], v173 offset:21504
	ds_read_b128 v[238:241], v173 offset:22528
	ds_read_b128 v[242:245], v173 offset:23552
	global_load_lds_dwordx4 v[164:165], off
	s_add_i32 m0, s0, 0x2000
	s_add_u32 s0, s46, 0x40000
	v_lshl_add_u64 v[176:177], s[46:47], 0, v[136:137]
	s_addc_u32 s1, s47, 0
	s_add_i32 s12, s15, s73
	global_load_lds_dwordx4 v[176:177], off
	v_lshl_add_u64 v[178:179], s[0:1], 0, v[80:81]
	s_mov_b32 m0, s12
	v_lshl_add_u64 v[246:247], s[48:49], 0, v[138:139]
	global_load_lds_dwordx4 v[178:179], off
	v_lshl_add_u64 v[178:179], s[0:1], 0, v[136:137]
	s_add_i32 m0, s12, 0x2000
	s_nop 0
	global_load_lds_dwordx4 v[178:179], off
	v_lshl_add_u64 v[178:179], s[48:49], 0, v[140:141]
	s_waitcnt vmcnt(6)
	s_waitcnt lgkmcnt(0)
	s_barrier
; #define PG8_STAGE(bufoff, gbase, voff) do { _Pragma("unroll") for (int _i = 0; _i < 2; ++_i) \
;         __builtin_amdgcn_global_load_lds((const unsigned*)((const char*)(gbase) + (voff)[_i]), (LAS unsigned*)(lds + (bufoff) + ldsw + _i * 8192), 16, 0, 0); } while (0)
; #define PG8_LDA(dst, b, h) do { _Pragma("unroll") for (int m = 0; m < 4; ++m) _Pragma("unroll") for (int k = 0; k < 2; ++k) dst[m][k] = *(const LAS bf16x8*)(lds + PG8_SA(b, h) + aoff + m * 2048 + k * 1024); } while (0)
; #define PG8_LDB(dst, b, h) do { _Pragma("unroll") for (int n = 0; n < 2; ++n) _Pragma("unroll") for (int k = 0; k < 2; ++k) dst[n][k] = *(const LAS bf16x8*)(lds + PG8_SB(b, h) + boff + n * 2048 + k * 1024); } while (0)
; #define PG8_MMA(ai, bj, At, Bt) do { __builtin_amdgcn_s_setprio(1); _Pragma("unroll") for (int m = 0; m < 4; ++m) _Pragma("unroll") for (int n = 0; n < 2; ++n) _Pragma("unroll") for (int k = 0; k < 2; ++k) \
;         acc[ai][bj][m][n] = __builtin_amdgcn_mfma_f32_16x16x32_bf16(Bt[n][k], At[m][k], acc[ai][bj][m][n], 0, 0, 0); __builtin_amdgcn_s_setprio(0); } while (0)
; #define PG8_WAIT_V(n) asm volatile("s_waitcnt vmcnt(" #n ")" ::: "memory")
; #define PG8_WAIT_L(n) asm volatile("s_waitcnt lgkmcnt(" #n ")" ::: "memory")
; #define PG8_BAR __builtin_amdgcn_s_barrier()
; #define PG8_SCHED __builtin_amdgcn_sched_barrier(0)
; template <class Epi, bool ALIGN_EPI>
; __device__ __forceinline__ void gemm_phase(LAS unsigned char* lds, const Gemm g, const StaticOrder S, const Epi E) {
;     ...
;             PG8_LDA(At, 0, 1); PG8_STAGE(PG8_SB(0, 0), b2, voffB); PG8_STAGE(PG8_SB(0, 1), b2 + hstepB, voffB); PG8_STAGE(PG8_SA(0, 0), a2, voffA);
;             PG8_WAIT_V(8); PG8_WAIT_L(0); PG8_BAR; PG8_MMA(1, 0, At, B0); PG8_MMA(1, 1, At, B1); PG8_BAR; PG8_SCHED;
;             PG8_LDB(B0, 1, 0); PG8_LDB(B1, 1, 1); PG8_SCHED; PG8_LDA(At, 1, 0); PG8_STAGE(PG8_SA(0, 1), a2 + hstepA, voffA);
;             PG8_WAIT_V(8); PG8_WAIT_L(0); PG8_BAR; PG8_MMA(0, 0, At, B0); PG8_MMA(0, 1, At, B1); PG8_BAR; PG8_SCHED;
	s_setprio 1
	s_waitcnt lgkmcnt(0)
	v_mfma_f32_16x16x32_bf16 v[60:63], v[182:185], v[214:217], v[60:63]
	v_mfma_f32_16x16x32_bf16 v[52:55], v[190:193], v[214:217], v[52:55]
	v_mfma_f32_16x16x32_bf16 v[44:47], v[182:185], v[222:225], v[44:47]
	v_mfma_f32_16x16x32_bf16 v[40:43], v[190:193], v[222:225], v[40:43]
	v_mfma_f32_16x16x32_bf16 v[28:31], v[182:185], v[230:233], v[28:31]
	v_mfma_f32_16x16x32_bf16 v[20:23], v[190:193], v[230:233], v[20:23]
	v_mfma_f32_16x16x32_bf16 v[12:15], v[182:185], v[238:241], v[12:15]
	v_mfma_f32_16x16x32_bf16 v[8:11], v[190:193], v[238:241], v[8:11]
	s_mov_b32 m0, s24
	s_nop 0
	global_load_lds_dwordx4 v[178:179], off
	v_mfma_f32_16x16x32_bf16 v[60:63], v[186:189], v[218:221], v[60:63]
	v_mfma_f32_16x16x32_bf16 v[52:55], v[194:197], v[218:221], v[52:55]
	v_mfma_f32_16x16x32_bf16 v[44:47], v[186:189], v[226:229], v[44:47]
	v_mfma_f32_16x16x32_bf16 v[40:43], v[194:197], v[226:229], v[40:43]
	v_mfma_f32_16x16x32_bf16 v[28:31], v[186:189], v[234:237], v[28:31]
	v_mfma_f32_16x16x32_bf16 v[20:23], v[194:197], v[234:237], v[20:23]
	v_mfma_f32_16x16x32_bf16 v[12:15], v[186:189], v[242:245], v[12:15]
	v_mfma_f32_16x16x32_bf16 v[8:11], v[194:197], v[242:245], v[8:11]
	s_setprio 0
	s_setprio 1
	v_mfma_f32_16x16x32_bf16 v[56:59], v[198:201], v[214:217], v[56:59]
	v_mfma_f32_16x16x32_bf16 v[48:51], v[206:209], v[214:217], v[48:51]
	v_mfma_f32_16x16x32_bf16 v[36:39], v[198:201], v[222:225], v[36:39]
	v_mfma_f32_16x16x32_bf16 v[32:35], v[206:209], v[222:225], v[32:35]
	v_mfma_f32_16x16x32_bf16 v[24:27], v[198:201], v[230:233], v[24:27]
	v_mfma_f32_16x16x32_bf16 v[16:19], v[206:209], v[230:233], v[16:19]
	v_mfma_f32_16x16x32_bf16 v[4:7], v[198:201], v[238:241], v[4:7]
	v_mfma_f32_16x16x32_bf16 v[0:3], v[206:209], v[238:241], v[0:3]
	s_mov_b32 m0, s25
	s_nop 0
	global_load_lds_dwordx4 v[246:247], off
	v_mfma_f32_16x16x32_bf16 v[56:59], v[202:205], v[218:221], v[56:59]
	v_mfma_f32_16x16x32_bf16 v[48:51], v[210:213], v[218:221], v[48:51]
	v_mfma_f32_16x16x32_bf16 v[36:39], v[202:205], v[226:229], v[36:39]
	v_mfma_f32_16x16x32_bf16 v[32:35], v[210:213], v[226:229], v[32:35]
	v_mfma_f32_16x16x32_bf16 v[24:27], v[202:205], v[234:237], v[24:27]
	v_mfma_f32_16x16x32_bf16 v[16:19], v[210:213], v[234:237], v[16:19]
	v_mfma_f32_16x16x32_bf16 v[4:7], v[202:205], v[242:245], v[4:7]
	v_mfma_f32_16x16x32_bf16 v[0:3], v[210:213], v[242:245], v[0:3]
	s_setprio 0
	s_barrier
	s_add_i32 s12, 0, 0x18000
	v_add_u32_e32 v130, s12, v172
	s_add_i32 s15, 0, 0x1c000
	ds_read_b128 v[182:185], v130
	ds_read_b128 v[186:189], v130 offset:1024
	ds_read_b128 v[190:193], v130 offset:2048
	ds_read_b128 v[194:197], v130 offset:3072
	v_add_u32_e32 v130, s15, v172
	ds_read_b128 v[198:201], v130
	ds_read_b128 v[202:205], v130 offset:1024
	ds_read_b128 v[206:209], v130 offset:2048
	ds_read_b128 v[210:213], v130 offset:3072
	s_add_u32 s0, s48, 0x40000
	s_addc_u32 s1, s49, 0
	s_mov_b32 m0, s26
	v_lshl_add_u64 v[248:249], s[0:1], 0, v[140:141]
	ds_read_b128 v[214:217], v173 offset:32768
	ds_read_b128 v[218:221], v173 offset:33792
	ds_read_b128 v[222:225], v173 offset:34816
	ds_read_b128 v[226:229], v173 offset:35840
	ds_read_b128 v[230:233], v173 offset:36864
	ds_read_b128 v[234:237], v173 offset:37888
	ds_read_b128 v[238:241], v173 offset:38912
	ds_read_b128 v[242:245], v173 offset:39936
	global_load_lds_dwordx4 v[248:249], off
	v_lshl_add_u64 v[248:249], s[0:1], 0, v[138:139]
	s_mov_b32 m0, s27
	s_nop 0
	global_load_lds_dwordx4 v[248:249], off
	s_waitcnt vmcnt(8)
	s_waitcnt lgkmcnt(0)
	s_barrier
	s_setprio 1
	s_waitcnt lgkmcnt(0)
	v_mfma_f32_16x16x32_bf16 v[126:129], v[182:185], v[214:217], v[126:129]
	v_mfma_f32_16x16x32_bf16 v[118:121], v[190:193], v[214:217], v[118:121]
	v_mfma_f32_16x16x32_bf16 v[110:113], v[182:185], v[222:225], v[110:113]
	v_mfma_f32_16x16x32_bf16 v[106:109], v[190:193], v[222:225], v[106:109]
	v_mfma_f32_16x16x32_bf16 v[94:97], v[182:185], v[230:233], v[94:97]
	v_mfma_f32_16x16x32_bf16 v[86:89], v[190:193], v[230:233], v[86:89]
	v_mfma_f32_16x16x32_bf16 v[76:79], v[182:185], v[238:241], v[76:79]
	v_mfma_f32_16x16x32_bf16 v[72:75], v[190:193], v[238:241], v[72:75]
	v_mfma_f32_16x16x32_bf16 v[126:129], v[186:189], v[218:221], v[126:129]
	v_mfma_f32_16x16x32_bf16 v[118:121], v[194:197], v[218:221], v[118:121]
	v_mfma_f32_16x16x32_bf16 v[110:113], v[186:189], v[226:229], v[110:113]
	v_mfma_f32_16x16x32_bf16 v[106:109], v[194:197], v[226:229], v[106:109]
	v_mfma_f32_16x16x32_bf16 v[94:97], v[186:189], v[234:237], v[94:97]
	v_mfma_f32_16x16x32_bf16 v[86:89], v[194:197], v[234:237], v[86:89]
	v_mfma_f32_16x16x32_bf16 v[76:79], v[186:189], v[242:245], v[76:79]
	v_mfma_f32_16x16x32_bf16 v[72:75], v[194:197], v[242:245], v[72:75]
	s_setprio 0
	s_setprio 1
	v_mfma_f32_16x16x32_bf16 v[122:125], v[198:201], v[214:217], v[122:125]
	v_mfma_f32_16x16x32_bf16 v[114:117], v[206:209], v[214:217], v[114:117]
	v_mfma_f32_16x16x32_bf16 v[102:105], v[198:201], v[222:225], v[102:105]
	v_mfma_f32_16x16x32_bf16 v[98:101], v[206:209], v[222:225], v[98:101]
	v_mfma_f32_16x16x32_bf16 v[90:93], v[198:201], v[230:233], v[90:93]
	v_mfma_f32_16x16x32_bf16 v[82:85], v[206:209], v[230:233], v[82:85]
	v_mfma_f32_16x16x32_bf16 v[68:71], v[198:201], v[238:241], v[68:71]
	v_mfma_f32_16x16x32_bf16 v[64:67], v[206:209], v[238:241], v[64:67]
	v_mfma_f32_16x16x32_bf16 v[122:125], v[202:205], v[218:221], v[122:125]
	v_mfma_f32_16x16x32_bf16 v[114:117], v[210:213], v[218:221], v[114:117]
	v_mfma_f32_16x16x32_bf16 v[102:105], v[202:205], v[226:229], v[102:105]
	v_mfma_f32_16x16x32_bf16 v[98:101], v[210:213], v[226:229], v[98:101]
	v_mfma_f32_16x16x32_bf16 v[90:93], v[202:205], v[234:237], v[90:93]
	v_mfma_f32_16x16x32_bf16 v[82:85], v[210:213], v[234:237], v[82:85]
	v_mfma_f32_16x16x32_bf16 v[68:71], v[202:205], v[242:245], v[68:71]
	v_mfma_f32_16x16x32_bf16 v[64:67], v[210:213], v[242:245], v[64:67]
	s_setprio 0
	s_barrier
; #define PG8_STAGE(bufoff, gbase, voff) do { _Pragma("unroll") for (int _i = 0; _i < 2; ++_i) \
;         __builtin_amdgcn_global_load_lds((const unsigned*)((const char*)(gbase) + (voff)[_i]), (LAS unsigned*)(lds + (bufoff) + ldsw + _i * 8192), 16, 0, 0); } while (0)
; #define PG8_LDA(dst, b, h) do { _Pragma("unroll") for (int m = 0; m < 4; ++m) _Pragma("unroll") for (int k = 0; k < 2; ++k) dst[m][k] = *(const LAS bf16x8*)(lds + PG8_SA(b, h) + aoff + m * 2048 + k * 1024); } while (0)
; #define PG8_MMA(ai, bj, At, Bt) do { __builtin_amdgcn_s_setprio(1); _Pragma("unroll") for (int m = 0; m < 4; ++m) _Pragma("unroll") for (int n = 0; n < 2; ++n) _Pragma("unroll") for (int k = 0; k < 2; ++k) \
;         acc[ai][bj][m][n] = __builtin_amdgcn_mfma_f32_16x16x32_bf16(Bt[n][k], At[m][k], acc[ai][bj][m][n], 0, 0, 0); __builtin_amdgcn_s_setprio(0); } while (0)
; #define PG8_WAIT_V(n) asm volatile("s_waitcnt vmcnt(" #n ")" ::: "memory")
; #define PG8_WAIT_L(n) asm volatile("s_waitcnt lgkmcnt(" #n ")" ::: "memory")
; #define PG8_BAR __builtin_amdgcn_s_barrier()
; #define PG8_SCHED __builtin_amdgcn_sched_barrier(0)
; template <class Epi, bool ALIGN_EPI>
; __device__ __forceinline__ void gemm_phase(LAS unsigned char* lds, const Gemm g, const StaticOrder S, const Epi E) {
;     ...
;             PG8_LDA(At, 1, 1); PG8_STAGE(PG8_SB(1, 0), b3, voffB); PG8_STAGE(PG8_SB(1, 1), b3 + hstepB, voffB); PG8_STAGE(PG8_SA(1, 0), a3, voffA);
;             PG8_WAIT_V(8); PG8_WAIT_L(0); PG8_BAR; PG8_MMA(1, 0, At, B0); PG8_MMA(1, 1, At, B1); PG8_BAR; PG8_SCHED;
;         }
	s_add_i32 s0, s12, s73
	v_lshl_add_u64 v[164:165], v[164:165], 0, s[80:81]
	s_mov_b32 m0, s0
	ds_read_b128 v[214:217], v173 offset:49152
	ds_read_b128 v[218:221], v173 offset:50176
	ds_read_b128 v[222:225], v173 offset:51200
	ds_read_b128 v[226:229], v173 offset:52224
	ds_read_b128 v[230:233], v173 offset:53248
	ds_read_b128 v[234:237], v173 offset:54272
	ds_read_b128 v[238:241], v173 offset:55296
	ds_read_b128 v[242:245], v173 offset:56320
	global_load_lds_dwordx4 v[164:165], off
	s_add_i32 m0, s0, 0x2000
	s_add_u32 s0, s46, 0x40080
	v_lshl_add_u64 v[164:165], v[176:177], 0, s[80:81]
	s_addc_u32 s1, s47, 0
	s_add_i32 s12, s15, s73
	global_load_lds_dwordx4 v[164:165], off
	v_lshl_add_u64 v[164:165], s[0:1], 0, v[80:81]
	s_mov_b32 m0, s12
	s_nop 0
	global_load_lds_dwordx4 v[164:165], off
	v_lshl_add_u64 v[164:165], s[0:1], 0, v[136:137]
	s_add_i32 m0, s12, 0x2000
	s_nop 0
	global_load_lds_dwordx4 v[164:165], off
	v_lshl_add_u64 v[164:165], v[178:179], 0, s[80:81]
	v_lshl_add_u64 v[250:251], v[246:247], 0, s[80:81]
	s_waitcnt vmcnt(6)
	s_waitcnt lgkmcnt(0)
	s_barrier
	s_setprio 1
	s_waitcnt lgkmcnt(0)
	v_mfma_f32_16x16x32_bf16 v[60:63], v[182:185], v[214:217], v[60:63]
	v_mfma_f32_16x16x32_bf16 v[52:55], v[190:193], v[214:217], v[52:55]
	v_mfma_f32_16x16x32_bf16 v[44:47], v[182:185], v[222:225], v[44:47]
	v_mfma_f32_16x16x32_bf16 v[40:43], v[190:193], v[222:225], v[40:43]
	v_mfma_f32_16x16x32_bf16 v[28:31], v[182:185], v[230:233], v[28:31]
	v_mfma_f32_16x16x32_bf16 v[20:23], v[190:193], v[230:233], v[20:23]
	v_mfma_f32_16x16x32_bf16 v[12:15], v[182:185], v[238:241], v[12:15]
	v_mfma_f32_16x16x32_bf16 v[8:11], v[190:193], v[238:241], v[8:11]
	s_mov_b32 m0, s29
	s_nop 0
	global_load_lds_dwordx4 v[164:165], off
	v_mfma_f32_16x16x32_bf16 v[60:63], v[186:189], v[218:221], v[60:63]
	v_mfma_f32_16x16x32_bf16 v[52:55], v[194:197], v[218:221], v[52:55]
	v_mfma_f32_16x16x32_bf16 v[44:47], v[186:189], v[226:229], v[44:47]
	v_mfma_f32_16x16x32_bf16 v[40:43], v[194:197], v[226:229], v[40:43]
	v_mfma_f32_16x16x32_bf16 v[28:31], v[186:189], v[234:237], v[28:31]
	v_mfma_f32_16x16x32_bf16 v[20:23], v[194:197], v[234:237], v[20:23]
	v_mfma_f32_16x16x32_bf16 v[12:15], v[186:189], v[242:245], v[12:15]
	v_mfma_f32_16x16x32_bf16 v[8:11], v[194:197], v[242:245], v[8:11]
	s_setprio 0
	s_setprio 1
	v_mfma_f32_16x16x32_bf16 v[56:59], v[198:201], v[214:217], v[56:59]
	v_mfma_f32_16x16x32_bf16 v[48:51], v[206:209], v[214:217], v[48:51]
	v_mfma_f32_16x16x32_bf16 v[36:39], v[198:201], v[222:225], v[36:39]
	v_mfma_f32_16x16x32_bf16 v[32:35], v[206:209], v[222:225], v[32:35]
	v_mfma_f32_16x16x32_bf16 v[24:27], v[198:201], v[230:233], v[24:27]
	v_mfma_f32_16x16x32_bf16 v[16:19], v[206:209], v[230:233], v[16:19]
	v_mfma_f32_16x16x32_bf16 v[4:7], v[198:201], v[238:241], v[4:7]
	v_mfma_f32_16x16x32_bf16 v[0:3], v[206:209], v[238:241], v[0:3]
	s_mov_b32 m0, s30
	s_nop 0
	global_load_lds_dwordx4 v[250:251], off
	v_mfma_f32_16x16x32_bf16 v[56:59], v[202:205], v[218:221], v[56:59]
	v_mfma_f32_16x16x32_bf16 v[48:51], v[210:213], v[218:221], v[48:51]
	v_mfma_f32_16x16x32_bf16 v[36:39], v[202:205], v[226:229], v[36:39]
	v_mfma_f32_16x16x32_bf16 v[32:35], v[210:213], v[226:229], v[32:35]
	v_mfma_f32_16x16x32_bf16 v[24:27], v[202:205], v[234:237], v[24:27]
	v_mfma_f32_16x16x32_bf16 v[16:19], v[210:213], v[234:237], v[16:19]
	v_mfma_f32_16x16x32_bf16 v[4:7], v[202:205], v[242:245], v[4:7]
	v_mfma_f32_16x16x32_bf16 v[0:3], v[210:213], v[242:245], v[0:3]
	s_setprio 0
	s_barrier
	s_add_i32 s54, s54, 2
	s_add_u32 s40, s40, 0x100
	s_addc_u32 s41, s41, 0
	s_add_u32 s52, s52, 0x100
	s_addc_u32 s53, s53, 0
	s_cmp_gt_u32 s54, 13
	s_cbranch_scc0 .LBB0_604
	s_and_b64 vcc, exec, s[2:3]
	s_cbranch_vccz .LBB0_607
	s_barrier
